# attention tile loop: first two K-fragment ds_reads issued at the loop top ahead of the LDS-DMA issue block (latency overlap); rescale path drains and re-issues them
# speedup vs baseline: 1.0032x; 1.0032x over previous
.LBB0_424:
	v_add_u32_e32 v86, s76, v206
	ds_read_b128 v[82:85], v86
	ds_read_b128 v[86:89], v86 offset:4096
	s_cmp_gt_u32 s4, 33
	s_cselect_b64 s[6:7], -1, 0
	s_cmp_lt_u32 s4, 34
	s_cselect_b32 s20, s75, 0x230000
	s_lshl_b64 s[8:9], s[20:21], 1
	s_add_u32 s8, s36, s8
	s_addc_u32 s9, s37, s9
	s_add_i32 s5, s77, 0
	v_lshl_add_u64 v[80:81], v[180:181], 1, s[8:9]
	s_add_i32 s8, s5, s42
	s_mov_b32 s9, m0
	s_mov_b32 m0, s8
	s_nop 0
	global_load_lds_dwordx4 v[80:81], off
	s_mov_b32 m0, s9
	v_lshl_add_u64 v[80:81], v[176:177], 1, s[38:39]
	s_mov_b32 s8, m0
	s_mov_b32 m0, s67
	s_nop 0
	global_load_lds_dwordx4 v[80:81], off
	s_mov_b32 m0, s8
	v_lshl_add_u64 v[80:81], v[178:179], 1, s[38:39]
	s_mov_b32 s8, m0
	s_mov_b32 m0, s68
	s_nop 0
	global_load_lds_dwordx4 v[80:81], off
	s_mov_b32 m0, s8
	v_add_f32_e32 v81, 0x41000000, v195
	v_cmp_gt_f32_e32 vcc, v197, v81
	s_cbranch_vccz .LBB0_428
	s_waitcnt lgkmcnt(0)
	ds_bpermute_b32 v80, v204, v197
	v_max_f32_e32 v82, v197, v197
	s_waitcnt lgkmcnt(0)
	v_max_f32_e32 v80, v80, v80
	v_max_f32_e32 v80, v82, v80
	v_mov_b64_e32 v[96:97], v[78:79]
	v_cmp_gt_f32_e32 vcc, v80, v81
	v_mov_b64_e32 v[94:95], v[76:77]
	v_mov_b64_e32 v[92:93], v[74:75]
	v_mov_b64_e32 v[90:91], v[72:73]
	v_mov_b64_e32 v[88:89], v[70:71]
	v_mov_b64_e32 v[86:87], v[68:69]
	v_mov_b64_e32 v[84:85], v[66:67]
	v_mov_b64_e32 v[82:83], v[64:65]
	s_and_saveexec_b64 s[8:9], vcc
	s_cbranch_execz .LBB0_427
	v_sub_f32_e32 v65, v80, v195
	v_exp_f32_e64 v64, -v65
	v_xor_b32_e32 v82, 0x80000000, v80
	v_sub_f32_e32 v127, v127, v65
	v_sub_f32_e32 v126, v126, v65
	v_mul_f32_e32 v196, v196, v64
	v_pk_mul_f32 v[62:63], v[62:63], v[64:65] op_sel_hi:[1,0]
	v_pk_mul_f32 v[60:61], v[60:61], v[64:65] op_sel_hi:[1,0]
	v_pk_mul_f32 v[58:59], v[58:59], v[64:65] op_sel_hi:[1,0]
	v_pk_mul_f32 v[56:57], v[56:57], v[64:65] op_sel_hi:[1,0]
	v_pk_mul_f32 v[54:55], v[54:55], v[64:65] op_sel_hi:[1,0]
	v_pk_mul_f32 v[52:53], v[52:53], v[64:65] op_sel_hi:[1,0]
	v_pk_mul_f32 v[50:51], v[50:51], v[64:65] op_sel_hi:[1,0]
	v_pk_mul_f32 v[48:49], v[48:49], v[64:65] op_sel_hi:[1,0]
	v_pk_mul_f32 v[46:47], v[46:47], v[64:65] op_sel_hi:[1,0]
	v_pk_mul_f32 v[44:45], v[44:45], v[64:65] op_sel_hi:[1,0]
	v_pk_mul_f32 v[42:43], v[42:43], v[64:65] op_sel_hi:[1,0]
	v_pk_mul_f32 v[40:41], v[40:41], v[64:65] op_sel_hi:[1,0]
	v_pk_mul_f32 v[38:39], v[38:39], v[64:65] op_sel_hi:[1,0]
	v_pk_mul_f32 v[36:37], v[36:37], v[64:65] op_sel_hi:[1,0]
	v_pk_mul_f32 v[34:35], v[34:35], v[64:65] op_sel_hi:[1,0]
	v_pk_mul_f32 v[32:33], v[32:33], v[64:65] op_sel_hi:[1,0]
	v_pk_mul_f32 v[30:31], v[30:31], v[64:65] op_sel_hi:[1,0]
	v_pk_mul_f32 v[28:29], v[28:29], v[64:65] op_sel_hi:[1,0]
	v_pk_mul_f32 v[26:27], v[26:27], v[64:65] op_sel_hi:[1,0]
	v_pk_mul_f32 v[24:25], v[24:25], v[64:65] op_sel_hi:[1,0]
	v_pk_mul_f32 v[22:23], v[22:23], v[64:65] op_sel_hi:[1,0]
	v_pk_mul_f32 v[20:21], v[20:21], v[64:65] op_sel_hi:[1,0]
	v_pk_mul_f32 v[18:19], v[18:19], v[64:65] op_sel_hi:[1,0]
	v_pk_mul_f32 v[16:17], v[16:17], v[64:65] op_sel_hi:[1,0]
	v_pk_mul_f32 v[14:15], v[14:15], v[64:65] op_sel_hi:[1,0]
	v_pk_mul_f32 v[12:13], v[12:13], v[64:65] op_sel_hi:[1,0]
	v_pk_mul_f32 v[10:11], v[10:11], v[64:65] op_sel_hi:[1,0]
	v_pk_mul_f32 v[8:9], v[8:9], v[64:65] op_sel_hi:[1,0]
	v_pk_mul_f32 v[6:7], v[6:7], v[64:65] op_sel_hi:[1,0]
	v_pk_mul_f32 v[4:5], v[4:5], v[64:65] op_sel_hi:[1,0]
	v_pk_mul_f32 v[2:3], v[2:3], v[64:65] op_sel_hi:[1,0]
	v_pk_mul_f32 v[0:1], v[0:1], v[64:65] op_sel_hi:[1,0]
	v_sub_f32_e32 v125, v125, v65
	v_sub_f32_e32 v124, v124, v65
	v_sub_f32_e32 v123, v123, v65
	v_sub_f32_e32 v122, v122, v65
	v_sub_f32_e32 v121, v121, v65
	v_sub_f32_e32 v120, v120, v65
	v_sub_f32_e32 v119, v119, v65
	v_sub_f32_e32 v118, v118, v65
	v_sub_f32_e32 v117, v117, v65
	v_sub_f32_e32 v116, v116, v65
	v_sub_f32_e32 v115, v115, v65
	v_sub_f32_e32 v114, v114, v65
	v_sub_f32_e32 v113, v113, v65
	v_sub_f32_e32 v112, v112, v65
	v_sub_f32_e32 v159, v159, v65
	v_sub_f32_e32 v158, v158, v65
	v_sub_f32_e32 v157, v157, v65
	v_sub_f32_e32 v156, v156, v65
	v_sub_f32_e32 v155, v155, v65
	v_sub_f32_e32 v154, v154, v65
	v_sub_f32_e32 v153, v153, v65
	v_sub_f32_e32 v152, v152, v65
	v_sub_f32_e32 v151, v151, v65
	v_sub_f32_e32 v150, v150, v65
	v_sub_f32_e32 v149, v149, v65
	v_sub_f32_e32 v148, v148, v65
	v_sub_f32_e32 v147, v147, v65
	v_sub_f32_e32 v146, v146, v65
	v_sub_f32_e32 v145, v145, v65
	v_sub_f32_e32 v144, v144, v65
	v_add_f32_e32 v81, 0x41000000, v80
	v_mov_b32_e32 v83, v82
	v_mov_b32_e32 v84, v82
	v_mov_b32_e32 v85, v82
	v_mov_b32_e32 v86, v82
	v_mov_b32_e32 v87, v82
	v_mov_b32_e32 v88, v82
	v_mov_b32_e32 v89, v82
	v_mov_b32_e32 v90, v82
	v_mov_b32_e32 v91, v82
	v_mov_b32_e32 v92, v82
	v_mov_b32_e32 v93, v82
	v_mov_b32_e32 v94, v82
	v_mov_b32_e32 v95, v82
	v_mov_b32_e32 v96, v82
	v_mov_b32_e32 v97, v82
	v_mov_b32_e32 v79, v82
	v_mov_b32_e32 v78, v82
	v_mov_b32_e32 v77, v82
	v_mov_b32_e32 v76, v82
	v_mov_b32_e32 v75, v82
	v_mov_b32_e32 v74, v82
	v_mov_b32_e32 v73, v82
	v_mov_b32_e32 v72, v82
	v_mov_b32_e32 v71, v82
	v_mov_b32_e32 v70, v82
	v_mov_b32_e32 v69, v82
	v_mov_b32_e32 v68, v82
	v_mov_b32_e32 v67, v82
	v_mov_b32_e32 v66, v82
	v_mov_b32_e32 v65, v82
	v_mov_b32_e32 v64, v82
	v_mov_b32_e32 v195, v80
.LBB0_427:
	s_or_b64 exec, exec, s[8:9]
	v_mov_b32_e32 v80, v79
	v_mov_b64_e32 v[64:65], v[82:83]
	v_mov_b64_e32 v[66:67], v[84:85]
	v_mov_b64_e32 v[68:69], v[86:87]
	v_mov_b64_e32 v[70:71], v[88:89]
	v_mov_b64_e32 v[72:73], v[90:91]
	v_mov_b64_e32 v[74:75], v[92:93]
	v_mov_b64_e32 v[76:77], v[94:95]
	v_mov_b64_e32 v[78:79], v[96:97]
	v_add_u32_e32 v86, s76, v206
	ds_read_b128 v[82:85], v86
	ds_read_b128 v[86:89], v86 offset:4096
	s_branch .LBB0_429

.LBB0_429:
	s_add_i32 s8, s76, 0
	v_add_u32_e32 v90, s8, v207
	v_add_u32_e32 v94, s8, v208
	v_add_u32_e32 v194, s8, v209
	s_waitcnt lgkmcnt(1)
	v_mfma_f32_32x32x16_bf16 v[128:143], v[82:85], v[160:163], v[64:79]
	ds_read_b128 v[82:85], v90
	ds_read_b128 v[90:93], v90 offset:4096
	v_exp_f32_e32 v95, v112
	v_exp_f32_e32 v245, v113
	v_exp_f32_e32 v145, v145
	v_exp_f32_e32 v244, v115
	v_exp_f32_e32 v115, v149
	v_cvt_pk_bf16_f32 v112, v95, v245
	s_waitcnt lgkmcnt(2)
	v_mfma_f32_32x32x16_bf16 v[96:111], v[86:89], v[160:163], v[64:79]
	ds_read_b128 v[86:89], v94
	ds_read_b128 v[232:235], v94 offset:4096
	ds_read_b128 v[236:239], v194
	ds_read_b128 v[240:243], v194 offset:4096
	v_exp_f32_e32 v94, v114
	v_exp_f32_e32 v114, v117
	v_exp_f32_e32 v156, v156
	s_add_i32 s8, s77, s76
	v_cvt_pk_bf16_f32 v113, v94, v244
	s_cmpk_eq_i32 s8, 0x2000
	s_waitcnt lgkmcnt(5)
	v_mfma_f32_32x32x16_bf16 v[128:143], v[82:85], v[164:167], v[128:143]
	v_exp_f32_e32 v85, v144
	v_exp_f32_e32 v84, v146
	v_exp_f32_e32 v144, v147
	s_cselect_b32 s9, s71, 0x2000
	v_cvt_pk_bf16_f32 v82, v85, v145
	s_cmpk_lg_i32 s8, 0x6000
	s_cselect_b32 s76, s9, 0
	s_waitcnt lgkmcnt(4)
	v_mfma_f32_32x32x16_bf16 v[96:111], v[90:93], v[164:167], v[96:111]
	v_add_f32_e32 v90, v94, v244
	v_add_f32_e32 v91, v95, v245
	v_add_f32_e32 v92, v84, v144
	v_add_f32_e32 v93, v85, v145
	v_exp_f32_e32 v94, v120
	v_add_f32_e32 v90, v90, v92
	v_add_f32_e32 v91, v91, v93
	v_exp_f32_e32 v92, v116
	v_exp_f32_e32 v93, v148
	s_waitcnt lgkmcnt(3)
	v_mfma_f32_32x32x16_bf16 v[128:143], v[86:89], v[168:171], v[128:143]
	v_add_f32_e32 v87, v90, v91
	v_cvt_pk_bf16_f32 v83, v84, v144
	v_add_f32_e32 v84, v92, v114
	v_add_f32_e32 v85, v93, v115
	v_exp_f32_e32 v86, v119
	v_add_f32_e32 v89, v84, v85
	v_exp_f32_e32 v85, v118
	v_exp_f32_e32 v88, v150
	v_exp_f32_e32 v90, v151
	s_waitcnt lgkmcnt(2)
	v_mfma_f32_32x32x16_bf16 v[96:111], v[232:235], v[168:171], v[96:111]
	v_cvt_pk_bf16_f32 v114, v92, v114
	v_cvt_pk_bf16_f32 v84, v93, v115
	v_add_f32_e32 v95, v85, v86
	v_add_f32_e32 v233, v88, v90
	v_cvt_pk_bf16_f32 v115, v85, v86
	v_cvt_pk_bf16_f32 v85, v88, v90
	ds_read_b64_tr_b16 v[90:91], v213 offset:24576
	ds_read_b64_tr_b16 v[92:93], v213 offset:26624
	v_exp_f32_e32 v232, v121
	v_exp_f32_e32 v88, v152
	v_exp_f32_e32 v86, v153
	ds_read_b64_tr_b16 v[116:117], v214 offset:24576
	ds_read_b64_tr_b16 v[118:119], v214 offset:26624
	ds_read_b64_tr_b16 v[144:145], v213 offset:28672
	ds_read_b64_tr_b16 v[146:147], v213 offset:30720
	v_add_f32_e32 v120, v94, v232
	v_add_f32_e32 v121, v95, v233
	s_waitcnt lgkmcnt(4)
	v_mfma_f32_32x32x16_bf16 v[48:63], v[90:93], v[112:115], v[48:63]
	v_add_f32_e32 v90, v88, v86
	v_add_f32_e32 v91, v89, v87
	v_exp_f32_e32 v234, v122
	v_add_f32_e32 v152, v120, v90
	v_add_f32_e32 v153, v121, v91
	ds_read_b64_tr_b16 v[90:91], v215 offset:24576
	ds_read_b64_tr_b16 v[92:93], v215 offset:26624
	ds_read_b64_tr_b16 v[148:149], v214 offset:28672
	ds_read_b64_tr_b16 v[150:151], v214 offset:30720
	v_exp_f32_e32 v235, v154
	v_exp_f32_e32 v87, v124
	v_exp_f32_e32 v89, v125
	v_mfma_f32_32x32x16_bf16 v[128:143], v[236:239], v[172:175], v[128:143]
	v_exp_f32_e32 v236, v123
	v_exp_f32_e32 v237, v155
	v_add_f32_e32 v239, v152, v153
	v_exp_f32_e32 v238, v159
	s_min_u32 s8, s4, 32
	s_min_u32 s10, s4, 33
	s_lshl_b32 s8, s8, 17
	s_waitcnt lgkmcnt(6)
	v_mfma_f32_32x32x16_bf16 v[32:47], v[116:119], v[112:115], v[32:47]
	ds_read_b64_tr_b16 v[116:117], v248 offset:24576
	ds_read_b64_tr_b16 v[118:119], v248 offset:26624
	ds_read_b64_tr_b16 v[120:121], v215 offset:28672
	ds_read_b64_tr_b16 v[122:123], v215 offset:30720
	ds_read_b64_tr_b16 v[152:153], v248 offset:28672
	ds_read_b64_tr_b16 v[154:155], v248 offset:30720
	s_add_u32 s8, s36, s8
	s_addc_u32 s9, s37, 0
	s_waitcnt lgkmcnt(8)
	v_mfma_f32_32x32x16_bf16 v[16:31], v[90:93], v[112:115], v[16:31]
	v_add_f32_e32 v92, v234, v236
	v_add_f32_e32 v93, v235, v237
	v_cvt_pk_bf16_f32 v90, v94, v232
	v_add_f32_e32 v95, v92, v93
	v_cvt_pk_bf16_f32 v91, v234, v236
	v_cvt_pk_bf16_f32 v92, v87, v89
	v_exp_f32_e32 v94, v158
	s_waitcnt lgkmcnt(4)
	v_mfma_f32_32x32x16_bf16 v[0:15], v[116:119], v[112:115], v[0:15]
	v_exp_f32_e32 v112, v126
	v_exp_f32_e32 v114, v127
	v_add_f32_e32 v113, v87, v89
	v_max_f32_e32 v89, v128, v128
	v_cvt_pk_bf16_f32 v93, v112, v114
	s_nop 1
	v_mfma_f32_32x32x16_bf16 v[48:63], v[144:147], v[90:93], v[48:63]
	v_exp_f32_e32 v144, v157
	v_cvt_pk_bf16_f32 v147, v94, v238
	v_cvt_pk_bf16_f32 v145, v235, v237
	v_add_f32_e32 v115, v156, v144
	v_add_f32_e32 v112, v112, v114
	v_add_f32_e32 v113, v113, v115
	v_add_f32_e32 v114, v94, v238
	v_add_f32_e32 v115, v95, v239
	v_mfma_f32_32x32x16_bf16 v[32:47], v[148:151], v[90:93], v[32:47]
	v_add_f32_e32 v112, v112, v114
	v_add_f32_e32 v113, v113, v115
	v_cvt_pk_bf16_f32 v146, v156, v144
	v_add_f32_e32 v87, v112, v113
	ds_read_b64_tr_b16 v[112:113], v213 offset:32768
	ds_read_b64_tr_b16 v[114:115], v213 offset:34816
	v_add_f32_e32 v194, v196, v87
	v_max_f32_e32 v87, v129, v129
	v_max_f32_e32 v87, v89, v87
	s_waitcnt lgkmcnt(4)
	v_mfma_f32_32x32x16_bf16 v[16:31], v[120:123], v[90:93], v[16:31]
	v_max3_f32 v87, v87, v130, v131
	v_max3_f32 v87, v87, v132, v133
	v_max3_f32 v87, v87, v134, v135
	v_max3_f32 v87, v87, v136, v137
	v_max3_f32 v87, v87, v138, v139
	v_max3_f32 v87, v87, v140, v141
	v_max3_f32 v87, v87, v142, v143
	s_waitcnt lgkmcnt(2)
	v_mfma_f32_32x32x16_bf16 v[0:15], v[152:155], v[90:93], v[0:15]
	ds_read_b64_tr_b16 v[90:91], v214 offset:32768
	ds_read_b64_tr_b16 v[92:93], v214 offset:34816
	ds_read_b64_tr_b16 v[116:117], v213 offset:36864
	ds_read_b64_tr_b16 v[118:119], v213 offset:38912
	v_cvt_pk_bf16_f32 v144, v88, v86
	s_waitcnt lgkmcnt(4)
	v_mfma_f32_32x32x16_bf16 v[48:63], v[112:115], v[82:85], v[48:63]
	ds_read_b64_tr_b16 v[112:113], v215 offset:32768
	ds_read_b64_tr_b16 v[114:115], v215 offset:34816
	ds_read_b64_tr_b16 v[120:121], v214 offset:36864
	ds_read_b64_tr_b16 v[122:123], v214 offset:38912
	s_waitcnt lgkmcnt(6)
	v_mfma_f32_32x32x16_bf16 v[32:47], v[90:93], v[82:85], v[32:47]
	ds_read_b64_tr_b16 v[90:91], v248 offset:32768
	ds_read_b64_tr_b16 v[92:93], v248 offset:34816
	ds_read_b64_tr_b16 v[124:125], v215 offset:36864
	ds_read_b64_tr_b16 v[126:127], v215 offset:38912
	v_mfma_f32_32x32x16_bf16 v[96:111], v[240:243], v[172:175], v[96:111]
	s_waitcnt lgkmcnt(6)
	v_mfma_f32_32x32x16_bf16 v[16:31], v[112:115], v[82:85], v[16:31]
	ds_read_b64_tr_b16 v[112:113], v248 offset:36864
	ds_read_b64_tr_b16 v[114:115], v248 offset:38912
	s_nop 7
	v_max3_f32 v87, v87, v96, v97
	v_max3_f32 v87, v87, v98, v99
	s_waitcnt vmcnt(0)
	s_waitcnt lgkmcnt(0)
	s_barrier
	v_mfma_f32_32x32x16_bf16 v[0:15], v[90:93], v[82:85], v[0:15]
	v_lshl_add_u64 v[82:83], v[180:181], 1, s[8:9]
	s_add_i32 s8, s43, s76
	v_lshl_add_u64 v[82:83], v[82:83], 0, s[24:25]
	s_mov_b32 s9, m0
	s_mov_b32 m0, s8
	s_nop 0
	global_load_lds_dwordx4 v[82:83], off
	s_mov_b32 m0, s9
	s_lshl_b32 s8, s10, 17
	v_max3_f32 v87, v87, v100, v101
	s_add_u32 s8, s26, s8
	v_mfma_f32_32x32x16_bf16 v[48:63], v[116:119], v[144:147], v[48:63]
	v_max3_f32 v87, v87, v102, v103
	s_addc_u32 s9, s27, 0
	v_max3_f32 v87, v87, v104, v105
	s_add_u32 s8, s8, 0x40000
	v_max3_f32 v87, v87, v106, v107
	s_addc_u32 s9, s9, 0
	v_max3_f32 v87, v87, v108, v109
	v_mfma_f32_32x32x16_bf16 v[32:47], v[120:123], v[144:147], v[32:47]
	v_lshl_add_u64 v[82:83], v[176:177], 1, s[8:9]
	s_mov_b32 s10, m0
	s_mov_b32 m0, s65
	s_nop 0
	global_load_lds_dwordx4 v[82:83], off
	s_mov_b32 m0, s10
	v_max3_f32 v87, v87, v110, v111
	v_lshl_add_u64 v[82:83], v[178:179], 1, s[8:9]
	s_mov_b32 s8, m0
	s_mov_b32 m0, s66
	s_nop 0
	global_load_lds_dwordx4 v[82:83], off
	s_mov_b32 m0, s8
	v_add_f32_e32 v87, v195, v87
	v_cmp_gt_f32_e32 vcc, v87, v81
	v_mfma_f32_32x32x16_bf16 v[16:31], v[124:127], v[144:147], v[16:31]
	v_mfma_f32_32x32x16_bf16 v[0:15], v[112:115], v[144:147], v[0:15]
	s_cbranch_vccz .LBB0_423
	ds_bpermute_b32 v82, v204, v87
	v_max_f32_e32 v83, v87, v87
	s_waitcnt lgkmcnt(0)
	v_max_f32_e32 v82, v82, v82
	v_max_f32_e32 v112, v83, v82
	v_cmp_gt_f32_e32 vcc, v112, v81
	s_and_saveexec_b64 s[8:9], vcc
	s_cbranch_execz .LBB0_422
	v_sub_f32_e32 v65, v112, v195
	v_exp_f32_e64 v64, -v65
	v_xor_b32_e32 v80, 0x80000000, v112
	v_mov_b32_e32 v81, v80
	v_sub_f32_e32 v128, v128, v65
	v_mul_f32_e32 v194, v194, v64
	v_pk_mul_f32 v[62:63], v[62:63], v[64:65] op_sel_hi:[1,0]
	v_pk_mul_f32 v[60:61], v[60:61], v[64:65] op_sel_hi:[1,0]
	v_pk_mul_f32 v[58:59], v[58:59], v[64:65] op_sel_hi:[1,0]
	v_pk_mul_f32 v[56:57], v[56:57], v[64:65] op_sel_hi:[1,0]
	v_pk_mul_f32 v[54:55], v[54:55], v[64:65] op_sel_hi:[1,0]
	v_pk_mul_f32 v[52:53], v[52:53], v[64:65] op_sel_hi:[1,0]
	v_pk_mul_f32 v[50:51], v[50:51], v[64:65] op_sel_hi:[1,0]
	v_pk_mul_f32 v[48:49], v[48:49], v[64:65] op_sel_hi:[1,0]
	v_pk_mul_f32 v[46:47], v[46:47], v[64:65] op_sel_hi:[1,0]
	v_pk_mul_f32 v[44:45], v[44:45], v[64:65] op_sel_hi:[1,0]
	v_pk_mul_f32 v[42:43], v[42:43], v[64:65] op_sel_hi:[1,0]
	v_pk_mul_f32 v[40:41], v[40:41], v[64:65] op_sel_hi:[1,0]
	v_pk_mul_f32 v[38:39], v[38:39], v[64:65] op_sel_hi:[1,0]
	v_pk_mul_f32 v[36:37], v[36:37], v[64:65] op_sel_hi:[1,0]
	v_pk_mul_f32 v[34:35], v[34:35], v[64:65] op_sel_hi:[1,0]
	v_pk_mul_f32 v[32:33], v[32:33], v[64:65] op_sel_hi:[1,0]
	v_pk_mul_f32 v[30:31], v[30:31], v[64:65] op_sel_hi:[1,0]
	v_pk_mul_f32 v[28:29], v[28:29], v[64:65] op_sel_hi:[1,0]
	v_pk_mul_f32 v[26:27], v[26:27], v[64:65] op_sel_hi:[1,0]
	v_pk_mul_f32 v[24:25], v[24:25], v[64:65] op_sel_hi:[1,0]
	v_pk_mul_f32 v[22:23], v[22:23], v[64:65] op_sel_hi:[1,0]
	v_pk_mul_f32 v[20:21], v[20:21], v[64:65] op_sel_hi:[1,0]
	v_pk_mul_f32 v[18:19], v[18:19], v[64:65] op_sel_hi:[1,0]
	v_pk_mul_f32 v[16:17], v[16:17], v[64:65] op_sel_hi:[1,0]
	v_pk_mul_f32 v[14:15], v[14:15], v[64:65] op_sel_hi:[1,0]
	v_pk_mul_f32 v[12:13], v[12:13], v[64:65] op_sel_hi:[1,0]
	v_pk_mul_f32 v[10:11], v[10:11], v[64:65] op_sel_hi:[1,0]
	v_pk_mul_f32 v[8:9], v[8:9], v[64:65] op_sel_hi:[1,0]
	v_pk_mul_f32 v[6:7], v[6:7], v[64:65] op_sel_hi:[1,0]
	v_pk_mul_f32 v[4:5], v[4:5], v[64:65] op_sel_hi:[1,0]
	v_pk_mul_f32 v[2:3], v[2:3], v[64:65] op_sel_hi:[1,0]
	v_pk_mul_f32 v[0:1], v[0:1], v[64:65] op_sel_hi:[1,0]
	v_sub_f32_e32 v129, v129, v65
	v_sub_f32_e32 v130, v130, v65
	v_sub_f32_e32 v131, v131, v65
	v_sub_f32_e32 v132, v132, v65
	v_sub_f32_e32 v133, v133, v65
	v_sub_f32_e32 v134, v134, v65
	v_sub_f32_e32 v135, v135, v65
	v_sub_f32_e32 v136, v136, v65
	v_sub_f32_e32 v137, v137, v65
	v_sub_f32_e32 v138, v138, v65
	v_sub_f32_e32 v139, v139, v65
	v_sub_f32_e32 v140, v140, v65
	v_sub_f32_e32 v141, v141, v65
	v_sub_f32_e32 v142, v142, v65
	v_sub_f32_e32 v143, v143, v65
	v_sub_f32_e32 v96, v96, v65
	v_sub_f32_e32 v97, v97, v65
	v_sub_f32_e32 v98, v98, v65
	v_sub_f32_e32 v99, v99, v65
	v_sub_f32_e32 v100, v100, v65
	v_sub_f32_e32 v101, v101, v65
	v_sub_f32_e32 v102, v102, v65
	v_sub_f32_e32 v103, v103, v65
	v_sub_f32_e32 v104, v104, v65
	v_sub_f32_e32 v105, v105, v65
	v_sub_f32_e32 v106, v106, v65
	v_sub_f32_e32 v107, v107, v65
	v_sub_f32_e32 v108, v108, v65
	v_sub_f32_e32 v109, v109, v65
	v_sub_f32_e32 v110, v110, v65
	v_sub_f32_e32 v111, v111, v65
	v_mov_b32_e32 v82, v80
	v_mov_b32_e32 v83, v80
	v_mov_b32_e32 v84, v80
	v_mov_b32_e32 v85, v80
	v_mov_b32_e32 v86, v80
	v_mov_b32_e32 v87, v80
	v_mov_b32_e32 v88, v80
	v_mov_b32_e32 v89, v80
	v_mov_b32_e32 v90, v80
	v_mov_b32_e32 v91, v80
	v_mov_b32_e32 v92, v80
	v_mov_b32_e32 v93, v80
	v_mov_b32_e32 v94, v80
	v_mov_b32_e32 v95, v80
	v_mov_b64_e32 v[64:65], v[80:81]
	v_mov_b32_e32 v195, v112
	v_mov_b64_e32 v[66:67], v[82:83]
	v_mov_b64_e32 v[68:69], v[84:85]
	v_mov_b64_e32 v[70:71], v[86:87]
	v_mov_b64_e32 v[72:73], v[88:89]
	v_mov_b64_e32 v[74:75], v[90:91]
	v_mov_b64_e32 v[76:77], v[92:93]
	v_mov_b64_e32 v[78:79], v[94:95]
	s_branch .LBB0_422
